# GLA loop with 2-step prefetch; dots: h-unpack overlapped with first gather
# speedup vs baseline: 1.0033x; 1.0033x over previous
; template <int DK>
; DI void scan_wg(const Params& p, char* smem, int grp, int dir, int hb) {
;   constexpr int NT = DK / 32, NF = DK / 16;
;   constexpr int QS = DK + 8;
;   constexpr int KTS = 40;
;   constexpr int OFF_K = 32 * QS * 2, OFF_KT = 2 * 32 * QS * 2, OFF_D = OFF_KT + DK * KTS * 2, BUFB = OFF_D + DK * 4;
;   constexpr int QN = DK / 64;
;   constexpr int CPR = DK / 8;
;   static_assert(2 * BUFB <= LDS_BYTES, "scan LDS");
;   const int tid = otid(), vs = tid >> 6, lane = tid & 63, r = lane & 31, h = lane >> 5;
;   const int b = hb >> 2, head = hb & 3;
;   const size_t chain = (size_t)dir * 16 + hb;
;   const u16* Qb = (const u16*)(p.S + (DK == 128 ? OFF_HQ : OFF_GQ)) + chain * LPOS * DK;
;   const u16* Kb = (const u16*)(p.S + (DK == 128 ? OFF_HK : OFF_GK)) + chain * LPOS * DK;
;   const u16* KTb = (const u16*)(p.S + (DK == 128 ? OFF_HKT : OFF_GKT)) + chain * NBLK * DK * 32;
;   const u16* VTb = (const u16*)(p.S + (DK == 128 ? OFF_HVT : OFF_GVT)) + (size_t)hb * NBLK * 128 * 32 + (vs * 32 + r) * 32 + h * 8;
;   const float* Db = (const float*)(p.S + (DK == 128 ? OFF_HD : OFF_GD)) + chain * NBLK * DK;
;   u16* Ob = p.U + (size_t)dir * NROW * D + grp * 512 + head * 128 + vs * 32;
;   f32x16 S[NT];
; #pragma unroll
;   for (int kt = 0; kt < NT; kt++)
; #pragma unroll
;     for (int e = 0; e < 16; e++) S[kt][e] = 0.f;
;   bf16x8 sq[QN], sk[QN], skt[QN], vn0, vn1;
;   float4 sd = make_float4(0.f, 0.f, 0.f, 0.f);
;   auto blk_of = [&](int step) { return dir ? (step < 8 ? 7 - step : 271 - step) : step; };
;   auto gload = [&](int step) {
;     const size_t pos0 = (size_t)blk_of(step) * 32;
; #pragma unroll
;     for (int i = 0; i < QN; i++) {
;       const int id = tid + i * 256;
;       sq[i] = *(const bf16x8*)(Qb + (pos0 + id / CPR) * DK + (id % CPR) * 8);
;       sk[i] = *(const bf16x8*)(Kb + (pos0 + id / CPR) * DK + (id % CPR) * 8);
;       skt[i] = *(const bf16x8*)(KTb + (size_t)blk_of(step) * DK * 32 + id * 8);
;     }
;     if (tid < DK / 4) sd = *(const float4*)(Db + (size_t)blk_of(step) * DK + tid * 4);
;     vn0 = *(const bf16x8*)(VTb + (size_t)blk_of(step) * 128 * 32);
;     vn1 = *(const bf16x8*)(VTb + (size_t)blk_of(step) * 128 * 32 + 16);
;   };
;   auto lstore = [&](int buf) {
;     char* base = smem + buf * BUFB;
; #pragma unroll
;     for (int i = 0; i < QN; i++) {
;       const int id = tid + i * 256;
.LBB0_565:
	s_or_b64 exec, exec, s[4:5]
	v_ashrrev_i32_e32 v10, 1, v8
	s_movk_i32 s21, 0xffe0
	v_readlane_b32 s4, v251, 42
	v_bfi_b32 v11, s21, v10, v8
	s_add_u32 s4, s4, s75
	v_readlane_b32 s5, v251, 43
	s_waitcnt vmcnt(3)
	v_lshlrev_b32_e32 v12, 5, v11
	v_bfe_u32 v9, v8, 5, 1
	s_addc_u32 s5, s5, 0
	v_ashrrev_i32_e32 v13, 31, v12
	v_lshl_add_u64 v[12:13], v[12:13], 1, s[4:5]
	v_lshlrev_b32_e32 v196, 4, v9
	v_lshl_add_u64 v[122:123], v[12:13], 0, v[196:197]
	s_lshl_b32 s24, s20, 13
	v_lshl_add_u64 v[12:13], v[122:123], 0, s[24:25]
	global_load_dwordx4 v[84:87], v[12:13], off
	global_load_dwordx4 v[80:83], v[12:13], off offset:32
	s_movk_i32 s4, 0x90
	v_mul_lo_u32 v6, v6, s4
	s_waitcnt vmcnt(15)
	v_lshl_add_u32 v134, v7, 4, v6
	v_lshrrev_b32_e32 v6, 2, v8
	v_mul_lo_u32 v6, v6, 40
	v_and_b32_e32 v7, 24, v2
	v_add_lshl_u32 v135, v6, v7, 1
	s_waitcnt vmcnt(14)
	v_lshlrev_b32_e32 v136, 4, v8
	s_waitcnt vmcnt(4)
	ds_write_b128 v134, v[64:67]
	s_waitcnt vmcnt(3)
	ds_write_b128 v134, v[68:71] offset:4608
	s_waitcnt vmcnt(2)
	ds_write_b128 v135, v[76:79] offset:9216
	s_and_saveexec_b64 s[4:5], s[40:41]
	ds_write_b128 v136, v[72:75] offset:14336
	s_or_b64 exec, exec, s[4:5]
	v_and_b32_e32 v137, 31, v8
	v_lshlrev_b32_e32 v138, 2, v9
	v_cmp_le_u32_e32 vcc, v138, v137
	v_lshl_add_u64 v[124:125], s[44:45], 0, v[0:1]
	v_lshl_add_u64 v[126:127], s[0:1], 0, v[0:1]
	v_cndmask_b32_e64 v0, 0, 1, vcc
	v_cmp_ge_u32_e32 vcc, v138, v137
	v_lshl_add_u64 v[128:129], v[2:3], 1, s[46:47]
	v_lshl_add_u64 v[132:133], v[4:5], 2, s[42:43]
	v_cndmask_b32_e64 v2, 0, 1, vcc
	v_cndmask_b32_e64 v0, v2, v0, s[38:39]
	v_and_b32_e32 v0, 1, v0
	v_cmp_eq_u32_e64 s[42:43], 1, v0
	v_or_b32_e32 v0, 1, v138
	v_cmp_lt_u32_e32 vcc, v138, v137
	s_add_u32 s4, s14, s33
	s_addc_u32 s5, s15, 0
	v_cndmask_b32_e64 v2, 0, 1, vcc
	v_cmp_ge_u32_e32 vcc, v0, v137
	s_lshl_b32 s21, s82, 8
	s_lshr_b32 s20, s82, 2
	v_cndmask_b32_e64 v0, 0, 1, vcc
	v_cndmask_b32_e64 v0, v0, v2, s[38:39]
	v_and_b32_e32 v0, 1, v0
	v_cmp_eq_u32_e64 s[44:45], 1, v0
	v_or_b32_e32 v0, 2, v138
	v_cmp_le_u32_e32 vcc, v0, v137
	s_and_b32 s21, s21, 0x300
	v_and_b32_e32 v6, 0xffffffe0, v10
	v_cndmask_b32_e64 v2, 0, 1, vcc
	v_cmp_ge_u32_e32 vcc, v0, v137
	s_add_u32 s4, s4, s21
	v_ashrrev_i32_e32 v7, 31, v6
	v_cndmask_b32_e64 v0, 0, 1, vcc
	v_cndmask_b32_e64 v0, v0, v2, s[38:39]
	v_and_b32_e32 v0, 1, v0
	v_cmp_eq_u32_e64 s[46:47], 1, v0
	v_or_b32_e32 v0, 3, v138
	v_cmp_le_u32_e32 vcc, v0, v137
	s_addc_u32 s5, s5, 0
	v_lshlrev_b32_e32 v196, 3, v9
	v_cndmask_b32_e64 v2, 0, 1, vcc
	v_cmp_ge_u32_e32 vcc, v0, v137
	v_lshl_add_u64 v[6:7], v[6:7], 1, s[4:5]
	v_mul_u32_u24_e32 v1, 0x48, v137
	v_cndmask_b32_e64 v0, 0, 1, vcc
	v_cndmask_b32_e64 v0, v0, v2, s[38:39]
	v_and_b32_e32 v0, 1, v0
	v_cmp_eq_u32_e64 s[48:49], 1, v0
	v_or_b32_e32 v0, 8, v138
	v_cmp_le_u32_e32 vcc, v0, v137
	s_lshl_b32 s74, s20, 8
	v_lshl_add_u64 v[130:131], v[6:7], 0, v[196:197]
	v_cndmask_b32_e64 v2, 0, 1, vcc
	v_cmp_ge_u32_e32 vcc, v0, v137
	s_lshl_b32 s24, s20, 13
	s_bitset1_b32 s74, 15
	v_cndmask_b32_e64 v0, 0, 1, vcc
	v_cndmask_b32_e64 v0, v0, v2, s[38:39]
	v_and_b32_e32 v0, 1, v0
	v_cmp_eq_u32_e64 s[50:51], 1, v0
	v_or_b32_e32 v0, 9, v138
	v_cmp_le_u32_e32 vcc, v0, v137
	v_mul_u32_u24_e32 v139, 0x50, v137
	s_mov_b32 s31, 0
	v_cndmask_b32_e64 v2, 0, 1, vcc
	v_cmp_ge_u32_e32 vcc, v0, v137
	s_mov_b32 s20, -1
	v_lshlrev_b32_e32 v140, 1, v1
	v_cndmask_b32_e64 v0, 0, 1, vcc
	v_cndmask_b32_e64 v0, v0, v2, s[38:39]
	v_and_b32_e32 v0, 1, v0
	v_cmp_eq_u32_e64 s[52:53], 1, v0
	v_or_b32_e32 v0, 10, v138
	v_cmp_le_u32_e32 vcc, v0, v137
	v_lshlrev_b32_e32 v141, 1, v196
	s_waitcnt lgkmcnt(0)
	v_cndmask_b32_e64 v2, 0, 1, vcc
	v_cmp_ge_u32_e32 vcc, v0, v137
	s_barrier
	s_nop 0
	v_cndmask_b32_e64 v0, 0, 1, vcc
	v_cndmask_b32_e64 v0, v0, v2, s[38:39]
	v_and_b32_e32 v0, 1, v0
	v_cmp_eq_u32_e64 s[54:55], 1, v0
	v_or_b32_e32 v0, 11, v138
	v_cmp_le_u32_e32 vcc, v0, v137
	s_nop 1
	v_cndmask_b32_e64 v2, 0, 1, vcc
	v_cmp_ge_u32_e32 vcc, v0, v137
	s_nop 1
	v_cndmask_b32_e64 v0, 0, 1, vcc
	v_cndmask_b32_e64 v0, v0, v2, s[38:39]
	v_and_b32_e32 v0, 1, v0
	v_cmp_eq_u32_e64 s[56:57], 1, v0
	v_or_b32_e32 v0, 16, v138
	v_cmp_le_u32_e32 vcc, v0, v137
	s_nop 1
	v_cndmask_b32_e64 v2, 0, 1, vcc
	v_cmp_ge_u32_e32 vcc, v0, v137
	s_nop 1
	v_cndmask_b32_e64 v0, 0, 1, vcc
	v_cndmask_b32_e64 v0, v0, v2, s[38:39]
	v_and_b32_e32 v0, 1, v0
	v_cmp_eq_u32_e64 s[58:59], 1, v0
	v_or_b32_e32 v0, 17, v138
	v_cmp_le_u32_e32 vcc, v0, v137
	s_nop 1
	v_cndmask_b32_e64 v2, 0, 1, vcc
	v_cmp_ge_u32_e32 vcc, v0, v137
	s_nop 1
	v_cndmask_b32_e64 v0, 0, 1, vcc
	v_cndmask_b32_e64 v0, v0, v2, s[38:39]
	v_and_b32_e32 v0, 1, v0
	v_cmp_eq_u32_e64 s[60:61], 1, v0
	v_or_b32_e32 v0, 18, v138
	v_cmp_le_u32_e32 vcc, v0, v137
	s_nop 1
	v_cndmask_b32_e64 v2, 0, 1, vcc
	v_cmp_ge_u32_e32 vcc, v0, v137
	s_nop 1
	v_cndmask_b32_e64 v0, 0, 1, vcc
	v_cndmask_b32_e64 v0, v0, v2, s[38:39]
	v_and_b32_e32 v0, 1, v0
	v_cmp_eq_u32_e64 s[62:63], 1, v0
	v_or_b32_e32 v0, 19, v138
	v_cmp_le_u32_e32 vcc, v0, v137
	s_nop 1
	v_cndmask_b32_e64 v2, 0, 1, vcc
	v_cmp_ge_u32_e32 vcc, v0, v137
	s_nop 1
	v_cndmask_b32_e64 v0, 0, 1, vcc
	v_cndmask_b32_e64 v0, v0, v2, s[38:39]
	v_and_b32_e32 v0, 1, v0
	v_cmp_eq_u32_e64 s[64:65], 1, v0
	v_or_b32_e32 v0, 24, v138
	v_cmp_le_u32_e32 vcc, v0, v137
	s_nop 1
	v_cndmask_b32_e64 v2, 0, 1, vcc
	v_cmp_ge_u32_e32 vcc, v0, v137
	s_nop 1
	v_cndmask_b32_e64 v0, 0, 1, vcc
	v_cndmask_b32_e64 v0, v0, v2, s[38:39]
	v_and_b32_e32 v0, 1, v0
	v_cmp_eq_u32_e64 s[66:67], 1, v0
	v_or_b32_e32 v0, 25, v138
	v_cmp_le_u32_e32 vcc, v0, v137
	s_nop 1
	v_cndmask_b32_e64 v2, 0, 1, vcc
	v_cmp_ge_u32_e32 vcc, v0, v137
	s_nop 1
; template <int DK>
; DI void scan_wg(const Params& p, char* smem, int grp, int dir, int hb) {
;     ...
;   f32x16 S[NT];
; #pragma unroll
;   for (int kt = 0; kt < NT; kt++)
; #pragma unroll
;     for (int e = 0; e < 16; e++) S[kt][e] = 0.f;
;   bf16x8 sq[QN], sk[QN], skt[QN], vn0, vn1;
;   float4 sd = make_float4(0.f, 0.f, 0.f, 0.f);
;   auto blk_of = [&](int step) { return dir ? (step < 8 ? 7 - step : 271 - step) : step; };
;   auto gload = [&](int step) {
;     const size_t pos0 = (size_t)blk_of(step) * 32;
; #pragma unroll
;     for (int i = 0; i < QN; i++) {
;       const int id = tid + i * 256;
;       sq[i] = *(const bf16x8*)(Qb + (pos0 + id / CPR) * DK + (id % CPR) * 8);
;       sk[i] = *(const bf16x8*)(Kb + (pos0 + id / CPR) * DK + (id % CPR) * 8);
;       skt[i] = *(const bf16x8*)(KTb + (size_t)blk_of(step) * DK * 32 + id * 8);
;     }
;     if (tid < DK / 4) sd = *(const float4*)(Db + (size_t)blk_of(step) * DK + tid * 4);
;     vn0 = *(const bf16x8*)(VTb + (size_t)blk_of(step) * 128 * 32);
;     vn1 = *(const bf16x8*)(VTb + (size_t)blk_of(step) * 128 * 32 + 16);
;   };
;   auto lstore = [&](int buf) {
;     char* base = smem + buf * BUFB;
; #pragma unroll
;     for (int i = 0; i < QN; i++) {
;       const int id = tid + i * 256;
;       *(bf16x8*)(base + ((id / CPR) * QS + (id % CPR) * 8) * 2) = sq[i];
;       *(bf16x8*)(base + OFF_K + ((id / CPR) * QS + (id % CPR) * 8) * 2) = sk[i];
;       *(bf16x8*)(base + OFF_KT + ((id >> 2) * KTS + (id & 3) * 8) * 2) = skt[i];
;     }
;     if (tid < DK / 4) *(float4*)(base + OFF_D + tid * 16) = sd;
;   };
;   __builtin_amdgcn_s_setprio(3);
;   __syncthreads();
;   gload(0);
;   lstore(0);
;   bf16x8 vf0 = vn0, vf1 = vn1;
;   __syncthreads();
; #pragma unroll 1
;   for (int step = 0; step < NBLK; step++) {
;     const int blk = blk_of(step);
;     if (step + 1 < NBLK) gload(step + 1);
;     const char* base = smem + (step & 1) * BUFB;
	v_cndmask_b32_e64 v0, 0, 1, vcc
	v_cndmask_b32_e64 v0, v0, v2, s[38:39]
	v_and_b32_e32 v0, 1, v0
	v_cmp_eq_u32_e64 s[68:69], 1, v0
	v_or_b32_e32 v0, 26, v138
	v_cmp_le_u32_e32 vcc, v0, v137
	s_nop 1
	v_cndmask_b32_e64 v2, 0, 1, vcc
	v_cmp_ge_u32_e32 vcc, v0, v137
	s_nop 1
	v_cndmask_b32_e64 v0, 0, 1, vcc
	v_cndmask_b32_e64 v0, v0, v2, s[38:39]
	v_and_b32_e32 v0, 1, v0
	v_cmp_eq_u32_e64 s[70:71], 1, v0
	v_or_b32_e32 v0, 27, v138
	v_cmp_le_u32_e32 vcc, v0, v137
	s_nop 1
	v_cndmask_b32_e64 v2, 0, 1, vcc
	v_cmp_ge_u32_e32 vcc, v0, v137
	s_nop 1
	v_cndmask_b32_e64 v0, 0, 1, vcc
	v_cndmask_b32_e64 v0, v0, v2, s[38:39]
	v_and_b32_e32 v0, 1, v0
	v_cmp_eq_u32_e64 s[72:73], 1, v0
	v_mov_b32_e32 v0, 0
	v_mov_b32_e32 v1, v0
	v_mov_b32_e32 v2, v0
	v_mov_b32_e32 v3, v0
	v_mov_b32_e32 v4, v0
	v_mov_b32_e32 v5, v0
	v_mov_b32_e32 v6, v0
	v_mov_b32_e32 v7, v0
	v_mov_b32_e32 v8, v0
	v_mov_b32_e32 v9, v0
	v_mov_b32_e32 v10, v0
	v_mov_b32_e32 v11, v0
	v_mov_b32_e32 v12, v0
	v_mov_b32_e32 v13, v0
	v_mov_b32_e32 v14, v0
	v_mov_b32_e32 v15, v0
	v_mov_b32_e32 v16, v0
	v_mov_b32_e32 v17, v0
	v_mov_b32_e32 v18, v0
	v_mov_b32_e32 v19, v0
	v_mov_b32_e32 v20, v0
	v_mov_b32_e32 v21, v0
	v_mov_b32_e32 v22, v0
	v_mov_b32_e32 v23, v0
	v_mov_b32_e32 v24, v0
	v_mov_b32_e32 v25, v0
	v_mov_b32_e32 v26, v0
	v_mov_b32_e32 v27, v0
	v_mov_b32_e32 v28, v0
	v_mov_b32_e32 v29, v0
	v_mov_b32_e32 v30, v0
	v_mov_b32_e32 v31, v0
	v_mov_b32_e32 v96, v0
	v_mov_b32_e32 v97, v0
	v_mov_b32_e32 v98, v0
	v_mov_b32_e32 v99, v0
	v_mov_b32_e32 v100, v0
	v_mov_b32_e32 v101, v0
	v_mov_b32_e32 v103, v0
	v_mov_b32_e32 v119, v0
	v_mov_b32_e32 v142, v0
	v_mov_b32_e32 v143, v0
	v_mov_b32_e32 v144, v0
	v_mov_b32_e32 v145, v0
	v_mov_b32_e32 v146, v0
	v_mov_b32_e32 v147, v0
	v_mov_b32_e32 v148, v0
	v_mov_b32_e32 v102, v0
	v_mov_b32_e32 v104, v0
	v_mov_b32_e32 v105, v0
	v_mov_b32_e32 v106, v0
	v_mov_b32_e32 v107, v0
	v_mov_b32_e32 v109, v0
	v_mov_b32_e32 v111, v0
	v_mov_b32_e32 v113, v0
	v_mov_b32_e32 v108, v0
	v_mov_b32_e32 v110, v0
	v_mov_b32_e32 v112, v0
	v_mov_b32_e32 v114, v0
	v_mov_b32_e32 v115, v0
	v_mov_b32_e32 v116, v0
	v_mov_b32_e32 v117, v0
	v_mov_b32_e32 v118, v0
	v_lshl_add_u64 v[124:125], v[120:121], 1, v[124:125]
	v_lshl_add_u64 v[126:127], v[120:121], 1, v[126:127]
	v_and_b32_e32 v253, 0x3c0, v220
	v_lshlrev_b32_e32 v253, 4, v253
	v_sub_u32_e32 v136, v136, v253
	v_sub_u32_e32 v254, 0, v253
	v_ashrrev_i32_e32 v255, 31, v254
	v_lshl_add_u64 v[132:133], v[254:255], 0, v[132:133]
	s_mov_b32 s40, 0xffff
	s_mov_b32 s41, 0
	s_movk_i32 s26, 0x800
	s_mov_b32 s20, 1
	s_cmp_lt_u32 s20, 8
	s_cselect_b32 s21, 7, 0x10f
	s_sub_i32 s21, s21, s20
	s_and_b64 vcc, s[38:39], exec
	s_cselect_b32 s20, s20, s21
	s_lshl_b32 s82, s20, 8
	s_mov_b32 s83, 0
	s_lshl_b32 s20, s20, 12
	s_mov_b32 s21, 0
	v_lshl_add_u64 v[170:171], v[132:133], 0, s[82:83]
	s_mov_b64 exec, s[40:41]
	global_load_dwordx4 v[206:209], v[170:171], off
	s_mov_b64 exec, -1
	v_lshl_add_u64 v[142:143], v[124:125], 0, s[20:21]
	global_load_dwordx4 v[198:201], v[142:143], off
	v_lshl_add_u64 v[144:145], v[126:127], 0, s[20:21]
	global_load_dwordx4 v[202:205], v[144:145], off
	v_lshl_add_u64 v[146:147], v[128:129], 0, s[20:21]
	global_load_dwordx4 v[210:213], v[146:147], off
	s_mov_b32 s20, 2
	s_cmp_lt_u32 s20, 8
	s_cselect_b32 s21, 7, 0x10f
	s_sub_i32 s21, s21, s20
	s_and_b64 vcc, s[38:39], exec
	s_cselect_b32 s20, s20, s21
	s_lshl_b32 s82, s20, 8
	s_mov_b32 s83, 0
	s_lshl_b32 s20, s20, 12
	s_mov_b32 s21, 0
	v_lshl_add_u64 v[170:171], v[132:133], 0, s[82:83]
	s_mov_b64 exec, s[40:41]
	global_load_dwordx4 v[72:75], v[170:171], off
	s_mov_b64 exec, -1
	v_lshl_add_u64 v[142:143], v[124:125], 0, s[20:21]
	global_load_dwordx4 v[64:67], v[142:143], off
	v_lshl_add_u64 v[144:145], v[126:127], 0, s[20:21]
	global_load_dwordx4 v[68:71], v[144:145], off
	v_lshl_add_u64 v[146:147], v[128:129], 0, s[20:21]
	global_load_dwordx4 v[76:79], v[146:147], off
	s_mov_b32 s4, 1
	s_cmp_lt_u32 s4, 8
	s_cselect_b32 s5, 7, 0x10f
	s_sub_i32 s5, s5, s4
	s_and_b64 vcc, s[38:39], exec
	s_cselect_b32 s4, s4, s5
	s_lshl_b32 s4, s4, 13
	s_mov_b32 s5, 0
	v_lshl_add_u64 v[218:219], v[122:123], 0, s[4:5]
	global_load_dwordx4 v[214:217], v[218:219], off
	global_load_dwordx4 v[230:233], v[218:219], off offset:32
	s_waitcnt vmcnt(0)
.Lgs_top:
	s_bitcmp1_b32 s31, 0
	s_cselect_b32 s0, 0x3900, 0
	s_cselect_b32 s1, 0, 0x3900
	s_add_i32 s4, s31, 2
	s_min_u32 s4, s4, 0x107
	s_cmp_lt_u32 s4, 8
	s_cselect_b32 s5, 7, 0x10f
	s_sub_i32 s5, s5, s4
	s_and_b64 vcc, s[38:39], exec
	s_cselect_b32 s4, s4, s5
	s_lshl_b32 s4, s4, 13
	s_mov_b32 s5, 0
	v_lshl_add_u64 v[218:219], v[122:123], 0, s[4:5]
	s_bitcmp1_b32 s31, 0
	s_cbranch_scc1 .Lgs_lv_odd
	global_load_dwordx4 v[88:91], v[218:219], off
	global_load_dwordx4 v[92:95], v[218:219], off offset:32
	s_branch .Lgs_lv_done
.Lgs_lv_odd:
	global_load_dwordx4 v[214:217], v[218:219], off
	global_load_dwordx4 v[230:233], v[218:219], off offset:32
.Lgs_lv_done:
	s_add_i32 s20, s31, 3
	s_min_u32 s20, s20, 0x107
	s_cmp_lt_u32 s20, 8
	s_cselect_b32 s21, 7, 0x10f
	s_sub_i32 s21, s21, s20
	s_and_b64 vcc, s[38:39], exec
	s_cselect_b32 s20, s20, s21
	s_lshl_b32 s82, s20, 8
	s_mov_b32 s83, 0
	s_lshl_b32 s20, s20, 12
	s_mov_b32 s21, 0
	s_waitcnt vmcnt(16)
	s_bitcmp1_b32 s31, 0
	s_cbranch_scc1 .Lgs_wl_odd
	v_add_u32_e32 v148, s1, v134
	v_add_u32_e32 v149, s1, v135
	v_add_u32_e32 v253, s1, v136
	ds_write_b128 v148, v[198:201]
	ds_write_b128 v148, v[202:205] offset:4608
	ds_write_b128 v149, v[210:213] offset:9216
	s_mov_b64 exec, s[40:41]
	ds_write_b128 v253, v[206:209] offset:14336
	s_mov_b64 exec, -1
	v_lshl_add_u64 v[170:171], v[132:133], 0, s[82:83]
	s_mov_b64 exec, s[40:41]
	global_load_dwordx4 v[206:209], v[170:171], off
	s_mov_b64 exec, -1
	v_lshl_add_u64 v[142:143], v[124:125], 0, s[20:21]
	global_load_dwordx4 v[198:201], v[142:143], off
	v_lshl_add_u64 v[144:145], v[126:127], 0, s[20:21]
	global_load_dwordx4 v[202:205], v[144:145], off
	v_lshl_add_u64 v[146:147], v[128:129], 0, s[20:21]
	global_load_dwordx4 v[210:213], v[146:147], off
	s_branch .Lgs_wl_done
; template <int DK>
; DI void scan_wg(const Params& p, char* smem, int grp, int dir, int hb) {
;     ...
;     const u16* Qs = (const u16*)base + r * QS + h * 8;
;     const u16* Ks = (const u16*)(base + OFF_K) + r * QS + h * 8;
;     const u16* KTs = (const u16*)(base + OFF_KT) + r * KTS + h * 8;
;     const float* Ds = (const float*)(base + OFF_D) + 4 * h;
;     bf16x8 qf[NF];
;     f32x16 P0, P1;
; #pragma unroll
;     for (int e = 0; e < 16; e++) { P0[e] = 0.f; P1[e] = 0.f; }
; #pragma unroll
;     for (int f = 0; f < NF; f += 2) {
;       qf[f] = *(const bf16x8*)(Qs + f * 16);
;       qf[f + 1] = *(const bf16x8*)(Qs + f * 16 + 16);
;       P0 = MFMA32(*(const bf16x8*)(Ks + f * 16), qf[f], P0);
;       P1 = MFMA32(*(const bf16x8*)(Ks + f * 16 + 16), qf[f + 1], P1);
;     }
; #pragma unroll
;     for (int e = 0; e < 16; e++) {
;       const int s = crow(e, h);
;       const bool keep = dir ? (s >= r) : (s <= r);
;       P0[e] = keep ? P0[e] + P1[e] : 0.f;
;     }
;     f32x16 oA, oB;
; #pragma unroll
;     for (int e = 0; e < 16; e++) { oA[e] = 0.f; oB[e] = 0.f; }
;     oA = MFMA32(vf0, pack_frag(P0, 0), oA);
;     oA = MFMA32(vf1, pack_frag(P0, 1), oA);
; #pragma unroll
;     for (int kt = 0; kt < NT; kt++) {
;       if (kt & 1) {
;         oA = MFMA32(pack_frag(S[kt], 0), qf[kt * 2], oA);
;         oA = MFMA32(pack_frag(S[kt], 1), qf[kt * 2 + 1], oA);
;       } else {
;         oB = MFMA32(pack_frag(S[kt], 0), qf[kt * 2], oB);
;         oB = MFMA32(pack_frag(S[kt], 1), qf[kt * 2 + 1], oB);
;       }
;     }
; #pragma unroll
;     for (int kt = 0; kt < NT; kt++) {
;       S[kt] = MFMA32(*(const bf16x8*)(KTs + kt * 32 * KTS), vf0, S[kt]);
;       S[kt] = MFMA32(*(const bf16x8*)(KTs + kt * 32 * KTS + 16), vf1, S[kt]);
; #pragma unroll
;       for (int g = 0; g < 4; g++) {
;         const float4 dv = *(const float4*)(Ds + kt * 32 + 8 * g);
;         S[kt][4 * g + 0] *= dv.x; S[kt][4 * g + 1] *= dv.y; S[kt][4 * g + 2] *= dv.z; S[kt][4 * g + 3] *= dv.w;
;       }
;     }
;     {
;       const int pos0 = blk * 32;
;       int rbase, rstride;
;       if (pos0 < CTX) { rbase = NLAT + b * CTX + pos0; rstride = 1; }
;       else if (grp == 0) { rbase = b * SEQ + pos0 - CTX; rstride = 1; }
;       else { const int pp = pos0 - CTX; rbase = b * SEQ + (pp & 127) * 64 + (pp >> 7); rstride = 64; }
;       u16* orow = Ob + (size_t)(rbase + r * rstride) * D + 4 * h;
.Lgs_wl_odd:
	v_add_u32_e32 v148, s1, v134
	v_add_u32_e32 v149, s1, v135
	v_add_u32_e32 v253, s1, v136
	ds_write_b128 v148, v[64:67]
	ds_write_b128 v148, v[68:71] offset:4608
	ds_write_b128 v149, v[76:79] offset:9216
	s_mov_b64 exec, s[40:41]
	ds_write_b128 v253, v[72:75] offset:14336
	s_mov_b64 exec, -1
	v_lshl_add_u64 v[170:171], v[132:133], 0, s[82:83]
	s_mov_b64 exec, s[40:41]
	global_load_dwordx4 v[72:75], v[170:171], off
	s_mov_b64 exec, -1
	v_lshl_add_u64 v[142:143], v[124:125], 0, s[20:21]
	global_load_dwordx4 v[64:67], v[142:143], off
	v_lshl_add_u64 v[144:145], v[126:127], 0, s[20:21]
	global_load_dwordx4 v[68:71], v[144:145], off
	v_lshl_add_u64 v[146:147], v[128:129], 0, s[20:21]
	global_load_dwordx4 v[76:79], v[146:147], off
.Lgs_wl_done:
	v_add3_u32 v166, s0, v140, v141
	v_add3_u32 v167, s0, v139, v141
	v_lshl_or_b32 v168, v138, 2, s0
	ds_read_b128 v[172:175], v166 offset:4608
	ds_read_b128 v[176:179], v166
	ds_read_b128 v[180:183], v166 offset:4640
	ds_read_b128 v[184:187], v166 offset:32
	ds_read_b128 v[188:191], v166 offset:4672
	ds_read_b128 v[192:195], v166 offset:64
	ds_read_b128 v[142:145], v166 offset:4704
	ds_read_b128 v[146:149], v166 offset:96
	s_waitcnt lgkmcnt(6)
	v_mfma_f32_32x32x16_bf16 v[32:47], v[172:175], v[176:179], 0
	v_cvt_pk_bf16_f32 v48, v0, v1
	v_cvt_pk_bf16_f32 v49, v2, v3
	v_cvt_pk_bf16_f32 v50, v4, v5
	v_cvt_pk_bf16_f32 v51, v6, v7
	s_waitcnt lgkmcnt(4)
	v_mfma_f32_32x32x16_bf16 v[32:47], v[180:183], v[184:187], v[32:47]
	v_cvt_pk_bf16_f32 v52, v8, v9
	v_cvt_pk_bf16_f32 v53, v10, v11
	v_cvt_pk_bf16_f32 v54, v12, v13
	v_cvt_pk_bf16_f32 v55, v14, v15
	s_waitcnt lgkmcnt(2)
	v_mfma_f32_32x32x16_bf16 v[32:47], v[188:191], v[192:195], v[32:47]
	ds_read_b128 v[150:153], v167 offset:9216
	ds_read_b128 v[154:157], v167 offset:9248
	ds_read_b128 v[158:161], v167 offset:11776
	ds_read_b128 v[162:165], v167 offset:11808
	v_cvt_pk_bf16_f32 v56, v16, v17
	v_cvt_pk_bf16_f32 v57, v18, v19
	v_cvt_pk_bf16_f32 v58, v20, v21
	v_cvt_pk_bf16_f32 v59, v22, v23
	s_waitcnt lgkmcnt(4)
	v_mfma_f32_32x32x16_bf16 v[32:47], v[142:145], v[146:149], v[32:47]
	v_cvt_pk_bf16_f32 v60, v24, v25
	v_cvt_pk_bf16_f32 v61, v26, v27
	v_cvt_pk_bf16_f32 v62, v28, v29
	v_cvt_pk_bf16_f32 v63, v30, v31
	s_waitcnt lgkmcnt(3)
	v_mfma_f32_32x32x16_bf16 v[0:15], v[150:153], v[84:87], v[0:15]
	ds_read_b128 v[96:99], v168 offset:14336
	ds_read_b128 v[100:103], v168 offset:14368
	ds_read_b128 v[104:107], v168 offset:14400
	ds_read_b128 v[108:111], v168 offset:14432
	ds_read_b128 v[112:115], v168 offset:14464
	ds_read_b128 v[116:119], v168 offset:14496
	ds_read_b128 v[234:237], v168 offset:14528
	ds_read_b128 v[238:241], v168 offset:14560
	s_waitcnt lgkmcnt(10)
	v_mfma_f32_32x32x16_bf16 v[0:15], v[154:157], v[80:83], v[0:15]
	v_cndmask_b32_e64 v32, 0, v32, s[42:43]
	v_cndmask_b32_e64 v33, 0, v33, s[44:45]
	v_cndmask_b32_e64 v34, 0, v34, s[46:47]
	v_cndmask_b32_e64 v35, 0, v35, s[48:49]
	v_cndmask_b32_e64 v36, 0, v36, s[50:51]
	v_cndmask_b32_e64 v37, 0, v37, s[52:53]
	s_waitcnt lgkmcnt(9)
	v_mfma_f32_32x32x16_bf16 v[16:31], v[158:161], v[84:87], v[16:31]
	v_cndmask_b32_e64 v38, 0, v38, s[54:55]
	v_cndmask_b32_e64 v39, 0, v39, s[56:57]
	v_cvt_pk_bf16_f32 v242, v32, v33
	v_cvt_pk_bf16_f32 v243, v34, v35
	v_cvt_pk_bf16_f32 v244, v36, v37
	v_cvt_pk_bf16_f32 v245, v38, v39
	v_cndmask_b32_e64 v40, 0, v40, s[58:59]
	v_cndmask_b32_e64 v41, 0, v41, s[60:61]
	v_cndmask_b32_e64 v42, 0, v42, s[62:63]
	s_waitcnt lgkmcnt(8)
	v_mfma_f32_32x32x16_bf16 v[16:31], v[162:165], v[80:83], v[16:31]
	ds_read_b128 v[172:175], v166
	ds_read_b128 v[176:179], v166 offset:32
	ds_read_b128 v[180:183], v166 offset:64
	ds_read_b128 v[184:187], v166 offset:96
	v_cndmask_b32_e64 v43, 0, v43, s[64:65]
	v_cndmask_b32_e64 v44, 0, v44, s[66:67]
	v_cndmask_b32_e64 v45, 0, v45, s[68:69]
	v_cndmask_b32_e64 v46, 0, v46, s[70:71]
	v_cndmask_b32_e64 v47, 0, v47, s[72:73]
	v_cvt_pk_bf16_f32 v246, v40, v41
	v_cvt_pk_bf16_f32 v247, v42, v43
	v_cvt_pk_bf16_f32 v248, v44, v45
	v_cvt_pk_bf16_f32 v249, v46, v47
	v_mfma_f32_32x32x16_bf16 v[32:47], v[84:87], v[242:245], 0
	s_waitcnt lgkmcnt(10)
	v_mul_f32_e32 v0, v0, v96
	v_mul_f32_e32 v1, v1, v97
	v_mul_f32_e32 v2, v2, v98
	v_mul_f32_e32 v3, v3, v99
	v_mul_f32_e32 v4, v4, v100
	v_mul_f32_e32 v5, v5, v101
	v_mul_f32_e32 v6, v6, v102
	v_mul_f32_e32 v7, v7, v103
	v_mfma_f32_32x32x16_bf16 v[32:47], v[80:83], v[246:249], v[32:47]
	s_waitcnt lgkmcnt(8)
	v_mul_f32_e32 v8, v8, v104
	v_mul_f32_e32 v9, v9, v105
	v_mul_f32_e32 v10, v10, v106
	v_mul_f32_e32 v11, v11, v107
	v_mul_f32_e32 v12, v12, v108
	v_mul_f32_e32 v13, v13, v109
	v_mul_f32_e32 v14, v14, v110
	v_mul_f32_e32 v15, v15, v111
	s_waitcnt lgkmcnt(3)
	v_mfma_f32_32x32x16_bf16 v[32:47], v[48:51], v[172:175], v[32:47]
	v_mul_f32_e32 v16, v16, v112
	v_mul_f32_e32 v17, v17, v113
	v_mul_f32_e32 v18, v18, v114
	v_mul_f32_e32 v19, v19, v115
	v_mul_f32_e32 v20, v20, v116
	v_mul_f32_e32 v21, v21, v117
	v_mul_f32_e32 v22, v22, v118
	v_mul_f32_e32 v23, v23, v119
	s_waitcnt lgkmcnt(2)
	v_mfma_f32_32x32x16_bf16 v[32:47], v[52:55], v[176:179], v[32:47]
	v_mul_f32_e32 v24, v24, v234
	v_mul_f32_e32 v25, v25, v235
	v_mul_f32_e32 v26, v26, v236
	v_mul_f32_e32 v27, v27, v237
	v_mul_f32_e32 v28, v28, v238
	v_mul_f32_e32 v29, v29, v239
	v_mul_f32_e32 v30, v30, v240
	v_mul_f32_e32 v31, v31, v241
	s_waitcnt lgkmcnt(1)
	v_mfma_f32_32x32x16_bf16 v[32:47], v[56:59], v[180:183], v[32:47]
	s_mov_b32 s4, s31
	s_cmp_lt_u32 s4, 8
	s_cselect_b32 s5, 7, 0x10f
	s_sub_i32 s5, s5, s4
	s_and_b64 vcc, s[38:39], exec
	s_cselect_b32 s4, s4, s5
	s_lshl_b32 s5, s4, 5
	s_lshl_b32 s27, s4, 11
	s_and_b32 s27, s27, 0x1800
	s_or_b32 s27, s27, s24
	s_add_i32 s21, s5, 0xffffff00
	s_lshr_b32 s21, s21, 7
	s_add_i32 s27, s27, s21
	s_add_i32 s21, s74, s5
	s_cmp_gt_i32 s4, 7
	s_cselect_b32 s21, s27, s21
	s_cselect_b32 s27, 64, 1
	v_mov_b32_e32 v253, s21
	s_waitcnt lgkmcnt(0)
	v_mfma_f32_32x32x16_bf16 v[32:47], v[60:63], v[184:187], v[32:47]
	v_mad_u32_u24 v253, s27, v137, v253
	v_mad_u64_u32 v[254:255], s[20:21], v253, s26, v[130:131]
	s_waitcnt vmcnt(14)
	s_bitcmp1_b32 s31, 0
	s_cbranch_scc1 .Lgs_cp_odd
	v_mov_b64_e32 v[84:85], v[214:215]
	v_mov_b64_e32 v[86:87], v[216:217]
	v_mov_b64_e32 v[80:81], v[230:231]
	v_mov_b64_e32 v[82:83], v[232:233]
	s_branch .Lgs_cp_done
; DI u32 pack2(float a, float b) { f32x2v v = {a, b}; return __builtin_bit_cast(u32, __builtin_convertvector(v, bf16x2v)); }
; template <int DK>
; DI void scan_wg(const Params& p, char* smem, int grp, int dir, int hb) {
;     ...
;       u16* orow = Ob + (size_t)(rbase + r * rstride) * D + 4 * h;
; #pragma unroll
;       for (int g = 0; g < 4; g++)
;         *(uint2*)(orow + 8 * g) = make_uint2(pack2(oA[4 * g] + oB[4 * g], oA[4 * g + 1] + oB[4 * g + 1]),
;                                              pack2(oA[4 * g + 2] + oB[4 * g + 2], oA[4 * g + 3] + oB[4 * g + 3]));
;     }
;     if (step + 1 < NBLK) lstore((step + 1) & 1);
;     vf0 = vn0; vf1 = vn1;
;     __syncthreads();
.Lgs_cp_odd:
	v_mov_b64_e32 v[84:85], v[88:89]
	v_mov_b64_e32 v[86:87], v[90:91]
	v_mov_b64_e32 v[80:81], v[92:93]
	v_mov_b64_e32 v[82:83], v[94:95]
.Lgs_cp_done:
	s_add_i32 s31, s31, 1
	s_nop 3
	v_cvt_pk_bf16_f32 v172, v32, v33
	v_cvt_pk_bf16_f32 v173, v34, v35
	v_cvt_pk_bf16_f32 v174, v36, v37
	v_cvt_pk_bf16_f32 v175, v38, v39
	v_cvt_pk_bf16_f32 v176, v40, v41
	v_cvt_pk_bf16_f32 v177, v42, v43
	v_cvt_pk_bf16_f32 v178, v44, v45
	v_cvt_pk_bf16_f32 v179, v46, v47
	global_store_dwordx2 v[254:255], v[172:173], off offset:1024
	global_store_dwordx2 v[254:255], v[174:175], off offset:1040
	global_store_dwordx2 v[254:255], v[176:177], off offset:1056
	global_store_dwordx2 v[254:255], v[178:179], off offset:1072
	s_cmpk_eq_i32 s31, 0x108
	s_waitcnt lgkmcnt(0)
	s_barrier
	s_cbranch_scc0 .Lgs_top
	s_waitcnt vmcnt(0)
	s_branch .LBB0_582

; template <int DK>
; DI void scan_wg(const Params& p, char* smem, int grp, int dir, int hb) {
;     ...
;     const u16* Qs = (const u16*)base + r * QS + h * 8;
;     const u16* Ks = (const u16*)(base + OFF_K) + r * QS + h * 8;
;     const u16* KTs = (const u16*)(base + OFF_KT) + r * KTS + h * 8;
;     const float* Ds = (const float*)(base + OFF_D) + 4 * h;
;     bf16x8 qf[NF];
;     f32x16 P0, P1;
; #pragma unroll
;     for (int e = 0; e < 16; e++) { P0[e] = 0.f; P1[e] = 0.f; }
; #pragma unroll
;     for (int f = 0; f < NF; f += 2) {
;       qf[f] = *(const bf16x8*)(Qs + f * 16);
;       qf[f + 1] = *(const bf16x8*)(Qs + f * 16 + 16);
;       P0 = MFMA32(*(const bf16x8*)(Ks + f * 16), qf[f], P0);
;       P1 = MFMA32(*(const bf16x8*)(Ks + f * 16 + 16), qf[f + 1], P1);
;     }
; #pragma unroll
;     for (int e = 0; e < 16; e++) {
;       const int s = crow(e, h);
;       const bool keep = dir ? (s >= r) : (s <= r);
;       P0[e] = keep ? P0[e] + P1[e] : 0.f;
;     }
;     f32x16 oA, oB;
; #pragma unroll
;     for (int e = 0; e < 16; e++) { oA[e] = 0.f; oB[e] = 0.f; }
;     oA = MFMA32(vf0, pack_frag(P0, 0), oA);
;     oA = MFMA32(vf1, pack_frag(P0, 1), oA);
; #pragma unroll
;     for (int kt = 0; kt < NT; kt++) {
;       if (kt & 1) {
;         oA = MFMA32(pack_frag(S[kt], 0), qf[kt * 2], oA);
;         oA = MFMA32(pack_frag(S[kt], 1), qf[kt * 2 + 1], oA);
;       } else {
;         oB = MFMA32(pack_frag(S[kt], 0), qf[kt * 2], oB);
;         oB = MFMA32(pack_frag(S[kt], 1), qf[kt * 2 + 1], oB);
;       }
;     }
; #pragma unroll
;     for (int kt = 0; kt < NT; kt++) {
;       S[kt] = MFMA32(*(const bf16x8*)(KTs + kt * 32 * KTS), vf0, S[kt]);
;       S[kt] = MFMA32(*(const bf16x8*)(KTs + kt * 32 * KTS + 16), vf1, S[kt]);
; #pragma unroll
;       for (int g = 0; g < 4; g++) {
;         const float4 dv = *(const float4*)(Ds + kt * 32 + 8 * g);
;         S[kt][4 * g + 0] *= dv.x; S[kt][4 * g + 1] *= dv.y; S[kt][4 * g + 2] *= dv.z; S[kt][4 * g + 3] *= dv.w;
;       }
;     }
;     {
;       const int pos0 = blk * 32;
;       int rbase, rstride;
;       if (pos0 < CTX) { rbase = NLAT + b * CTX + pos0; rstride = 1; }
;       else if (grp == 0) { rbase = b * SEQ + pos0 - CTX; rstride = 1; }
;       else { const int pp = pos0 - CTX; rbase = b * SEQ + (pp & 127) * 64 + (pp >> 7); rstride = 64; }
;       u16* orow = Ob + (size_t)(rbase + r * rstride) * D + 4 * h;
.Lhs_top:
	s_bitcmp1_b32 s30, 0
	s_cselect_b32 s0, 0x6e00, 0
	s_cselect_b32 s1, 0, 0x6e00
	s_add_i32 s4, s30, 1
	s_min_u32 s4, s4, 0x107
	s_cmp_lt_u32 s4, 8
	s_cselect_b32 s5, 7, 0x10f
	s_sub_i32 s5, s5, s4
	s_and_b64 vcc, s[38:39], exec
	s_cselect_b32 s4, s4, s5
	s_lshl_b32 s4, s4, 13
	s_mov_b32 s5, 0
	s_add_i32 s20, s30, 2
	s_min_u32 s20, s20, 0x107
	s_cmp_lt_u32 s20, 8
	s_cselect_b32 s21, 7, 0x10f
	s_sub_i32 s21, s21, s20
	s_and_b64 vcc, s[38:39], exec
	s_cselect_b32 s20, s20, s21
	s_lshl_b32 s82, s20, 9
	s_mov_b32 s83, 0
	s_lshl_b32 s20, s20, 13
	s_mov_b32 s21, 0
	s_waitcnt vmcnt(4)
	v_add_u32_e32 v242, s1, v230
	v_add_u32_e32 v243, s1, v231
	v_add_u32_e32 v244, s1, v232
	v_add_u32_e32 v245, s1, v233
	v_add_u32_e32 v246, s1, v234
	ds_write_b128 v242, v[96:99]
	ds_write_b128 v242, v[100:103] offset:8704
	ds_write_b128 v243, v[104:107] offset:17408
	ds_write_b128 v244, v[108:111]
	ds_write_b128 v244, v[116:119] offset:8704
	ds_write_b128 v245, v[120:123] offset:17408
	s_mov_b64 exec, s[40:41]
	ds_write_b128 v246, v[112:115] offset:27648
	s_mov_b64 exec, -1
	v_lshl_add_u64 v[80:81], v[206:207], 0, s[4:5]
	global_load_dwordx4 v[132:135], v[80:81], off
	global_load_dwordx4 v[136:139], v[80:81], off offset:32
	v_lshl_add_u64 v[82:83], v[218:219], 0, s[82:83]
	s_mov_b64 exec, s[40:41]
	global_load_dwordx4 v[112:115], v[82:83], off
	s_mov_b64 exec, -1
	v_lshl_add_u64 v[84:85], v[208:209], 0, s[20:21]
	global_load_dwordx4 v[96:99], v[84:85], off
	v_lshl_add_u64 v[86:87], v[210:211], 0, s[20:21]
	global_load_dwordx4 v[100:103], v[86:87], off
	v_lshl_add_u64 v[88:89], v[200:201], 0, s[20:21]
	global_load_dwordx4 v[104:107], v[88:89], off
	v_lshl_add_u64 v[90:91], v[212:213], 0, s[20:21]
	global_load_dwordx4 v[108:111], v[90:91], off
	v_lshl_add_u64 v[92:93], v[214:215], 0, s[20:21]
	global_load_dwordx4 v[116:119], v[92:93], off
	v_lshl_add_u64 v[94:95], v[204:205], 0, s[20:21]
	global_load_dwordx4 v[120:123], v[94:95], off
	v_add3_u32 v239, s0, v238, v196
	v_add3_u32 v240, s0, v237, v196
	v_lshl_or_b32 v241, v236, 2, s0
	ds_read_b128 v[172:175], v239 offset:8704
	ds_read_b128 v[176:179], v239
	ds_read_b128 v[180:183], v239 offset:8736
	ds_read_b128 v[184:187], v239 offset:32
	ds_read_b128 v[188:191], v239 offset:8768
	ds_read_b128 v[192:195], v239 offset:64
	s_waitcnt lgkmcnt(4)
	v_mfma_f32_32x32x16_bf16 v[64:79], v[172:175], v[176:179], 0
	ds_read_b128 v[172:175], v239 offset:8800
	ds_read_b128 v[176:179], v239 offset:96
	v_cvt_pk_bf16_f32 v140, v0, v1
	v_cvt_pk_bf16_f32 v141, v2, v3
	v_cvt_pk_bf16_f32 v142, v4, v5
	v_cvt_pk_bf16_f32 v143, v6, v7
	s_waitcnt lgkmcnt(4)
	v_mfma_f32_32x32x16_bf16 v[64:79], v[180:183], v[184:187], v[64:79]
	ds_read_b128 v[180:183], v239 offset:8832
	ds_read_b128 v[184:187], v239 offset:128
	v_cvt_pk_bf16_f32 v144, v8, v9
	v_cvt_pk_bf16_f32 v145, v10, v11
	v_cvt_pk_bf16_f32 v146, v12, v13
	v_cvt_pk_bf16_f32 v147, v14, v15
	s_waitcnt lgkmcnt(4)
	v_mfma_f32_32x32x16_bf16 v[64:79], v[188:191], v[192:195], v[64:79]
	ds_read_b128 v[188:191], v239 offset:8864
	ds_read_b128 v[192:195], v239 offset:160
	v_cvt_pk_bf16_f32 v148, v16, v17
	v_cvt_pk_bf16_f32 v149, v18, v19
	v_cvt_pk_bf16_f32 v150, v20, v21
	v_cvt_pk_bf16_f32 v151, v22, v23
	s_waitcnt lgkmcnt(4)
	v_mfma_f32_32x32x16_bf16 v[64:79], v[172:175], v[176:179], v[64:79]
	ds_read_b128 v[172:175], v239 offset:8896
	ds_read_b128 v[176:179], v239 offset:192
	v_cvt_pk_bf16_f32 v152, v24, v25
	v_cvt_pk_bf16_f32 v153, v26, v27
	v_cvt_pk_bf16_f32 v154, v28, v29
	v_cvt_pk_bf16_f32 v155, v30, v31
	s_waitcnt lgkmcnt(4)
	v_mfma_f32_32x32x16_bf16 v[64:79], v[180:183], v[184:187], v[64:79]
	ds_read_b128 v[180:183], v239 offset:8928
	ds_read_b128 v[184:187], v239 offset:224
	v_cvt_pk_bf16_f32 v156, v32, v33
	v_cvt_pk_bf16_f32 v157, v34, v35
	v_cvt_pk_bf16_f32 v158, v36, v37
	v_cvt_pk_bf16_f32 v159, v38, v39
	s_waitcnt lgkmcnt(4)
	v_mfma_f32_32x32x16_bf16 v[64:79], v[188:191], v[192:195], v[64:79]
	ds_read_b128 v[188:191], v240 offset:17408
	ds_read_b128 v[192:195], v240 offset:17440
	v_cvt_pk_bf16_f32 v160, v40, v41
	v_cvt_pk_bf16_f32 v161, v42, v43
	v_cvt_pk_bf16_f32 v162, v44, v45
	v_cvt_pk_bf16_f32 v163, v46, v47
	s_waitcnt lgkmcnt(4)
	v_mfma_f32_32x32x16_bf16 v[64:79], v[172:175], v[176:179], v[64:79]
	ds_read_b128 v[172:175], v240 offset:19968
	ds_read_b128 v[176:179], v240 offset:20000
	v_cvt_pk_bf16_f32 v164, v48, v49
	v_cvt_pk_bf16_f32 v165, v50, v51
	v_cvt_pk_bf16_f32 v166, v52, v53
	v_cvt_pk_bf16_f32 v167, v54, v55
	s_waitcnt lgkmcnt(4)
	v_mfma_f32_32x32x16_bf16 v[64:79], v[180:183], v[184:187], v[64:79]
	ds_read_b128 v[180:183], v240 offset:22528
	ds_read_b128 v[184:187], v240 offset:22560
	v_cvt_pk_bf16_f32 v168, v56, v57
	v_cvt_pk_bf16_f32 v169, v58, v59
	v_cvt_pk_bf16_f32 v170, v60, v61
	v_cvt_pk_bf16_f32 v171, v62, v63
	s_waitcnt lgkmcnt(5)
	v_mfma_f32_32x32x16_bf16 v[0:15], v[188:191], v[128:131], v[0:15]
	ds_read_b128 v[80:83], v241 offset:27648
	ds_read_b128 v[84:87], v241 offset:27680
	ds_read_b128 v[88:91], v241 offset:27712
	ds_read_b128 v[92:95], v241 offset:27744
	s_waitcnt lgkmcnt(8)
	v_mfma_f32_32x32x16_bf16 v[0:15], v[192:195], v[124:127], v[0:15]
	ds_read_b128 v[188:191], v240 offset:25088
	ds_read_b128 v[192:195], v240 offset:25120
	v_cndmask_b32_e64 v64, 0, v64, s[42:43]
	v_cndmask_b32_e64 v65, 0, v65, s[44:45]
	s_waitcnt lgkmcnt(9)
	v_mfma_f32_32x32x16_bf16 v[16:31], v[172:175], v[128:131], v[16:31]
	v_cndmask_b32_e64 v66, 0, v66, s[46:47]
	v_cndmask_b32_e64 v67, 0, v67, s[48:49]
	v_cndmask_b32_e64 v68, 0, v68, s[50:51]
	v_cndmask_b32_e64 v69, 0, v69, s[52:53]
	v_cndmask_b32_e64 v70, 0, v70, s[54:55]
	v_cndmask_b32_e64 v71, 0, v71, s[56:57]
	s_waitcnt lgkmcnt(8)
; DI u32 pack2(float a, float b) { f32x2v v = {a, b}; return __builtin_bit_cast(u32, __builtin_convertvector(v, bf16x2v)); }
; DI int crow(int i, int h) { return (i & 3) + 8 * (i >> 2) + 4 * h; }
; #define MFMA32(a, b, c) __builtin_amdgcn_mfma_f32_32x32x16_bf16((a), (b), (c), 0, 0, 0)
; template <int DK>
; DI void scan_wg(const Params& p, char* smem, int grp, int dir, int hb) {
;     ...
;     for (int e = 0; e < 16; e++) {
;       const int s = crow(e, h);
;       const bool keep = dir ? (s >= r) : (s <= r);
;       P0[e] = keep ? P0[e] + P1[e] : 0.f;
;     }
;     f32x16 oA, oB;
; #pragma unroll
;     for (int e = 0; e < 16; e++) { oA[e] = 0.f; oB[e] = 0.f; }
;     oA = MFMA32(vf0, pack_frag(P0, 0), oA);
;     oA = MFMA32(vf1, pack_frag(P0, 1), oA);
; #pragma unroll
;     for (int kt = 0; kt < NT; kt++) {
;       if (kt & 1) {
;         oA = MFMA32(pack_frag(S[kt], 0), qf[kt * 2], oA);
;         oA = MFMA32(pack_frag(S[kt], 1), qf[kt * 2 + 1], oA);
;       } else {
;         oB = MFMA32(pack_frag(S[kt], 0), qf[kt * 2], oB);
;         oB = MFMA32(pack_frag(S[kt], 1), qf[kt * 2 + 1], oB);
;       }
;     }
; #pragma unroll
;     for (int kt = 0; kt < NT; kt++) {
;       S[kt] = MFMA32(*(const bf16x8*)(KTs + kt * 32 * KTS), vf0, S[kt]);
;       S[kt] = MFMA32(*(const bf16x8*)(KTs + kt * 32 * KTS + 16), vf1, S[kt]);
; #pragma unroll
;       for (int g = 0; g < 4; g++) {
;         const float4 dv = *(const float4*)(Ds + kt * 32 + 8 * g);
;         S[kt][4 * g + 0] *= dv.x; S[kt][4 * g + 1] *= dv.y; S[kt][4 * g + 2] *= dv.z; S[kt][4 * g + 3] *= dv.w;
;       }
;     }
;     {
;       const int pos0 = blk * 32;
;       int rbase, rstride;
;       if (pos0 < CTX) { rbase = NLAT + b * CTX + pos0; rstride = 1; }
;       else if (grp == 0) { rbase = b * SEQ + pos0 - CTX; rstride = 1; }
;       else { const int pp = pos0 - CTX; rbase = b * SEQ + (pp & 127) * 64 + (pp >> 7); rstride = 64; }
;       u16* orow = Ob + (size_t)(rbase + r * rstride) * D + 4 * h;
; #pragma unroll
;       for (int g = 0; g < 4; g++)
;         *(uint2*)(orow + 8 * g) = make_uint2(pack2(oA[4 * g] + oB[4 * g], oA[4 * g + 1] + oB[4 * g + 1]),
;                                              pack2(oA[4 * g + 2] + oB[4 * g + 2], oA[4 * g + 3] + oB[4 * g + 3]));
;     }
;     if (step + 1 < NBLK) lstore((step + 1) & 1);
;     vf0 = vn0; vf1 = vn1;
	v_mfma_f32_32x32x16_bf16 v[16:31], v[176:179], v[124:127], v[16:31]
	ds_read_b128 v[172:175], v241 offset:27776
	ds_read_b128 v[176:179], v241 offset:27808
	v_cvt_pk_bf16_f32 v242, v64, v65
	v_cvt_pk_bf16_f32 v243, v66, v67
	v_cvt_pk_bf16_f32 v244, v68, v69
	v_cvt_pk_bf16_f32 v245, v70, v71
	v_cndmask_b32_e64 v72, 0, v72, s[58:59]
	s_waitcnt lgkmcnt(9)
	v_mfma_f32_32x32x16_bf16 v[32:47], v[180:183], v[128:131], v[32:47]
	v_cndmask_b32_e64 v73, 0, v73, s[60:61]
	v_cndmask_b32_e64 v74, 0, v74, s[62:63]
	v_cndmask_b32_e64 v75, 0, v75, s[64:65]
	v_cndmask_b32_e64 v76, 0, v76, s[66:67]
	v_cndmask_b32_e64 v77, 0, v77, s[68:69]
	v_cndmask_b32_e64 v78, 0, v78, s[70:71]
	s_waitcnt lgkmcnt(8)
	v_mfma_f32_32x32x16_bf16 v[32:47], v[184:187], v[124:127], v[32:47]
	ds_read_b128 v[180:183], v239
	ds_read_b128 v[184:187], v239 offset:32
	v_cndmask_b32_e64 v79, 0, v79, s[72:73]
	v_cvt_pk_bf16_f32 v246, v72, v73
	v_cvt_pk_bf16_f32 v247, v74, v75
	v_cvt_pk_bf16_f32 v248, v76, v77
	v_cvt_pk_bf16_f32 v249, v78, v79
	s_waitcnt lgkmcnt(5)
	v_mfma_f32_32x32x16_bf16 v[48:63], v[188:191], v[128:131], v[48:63]
	v_mul_f32_e32 v0, v0, v80
	v_mul_f32_e32 v1, v1, v81
	v_mul_f32_e32 v2, v2, v82
	v_mul_f32_e32 v3, v3, v83
	v_mul_f32_e32 v4, v4, v84
	v_mul_f32_e32 v5, v5, v85
	v_mul_f32_e32 v6, v6, v86
	v_mul_f32_e32 v7, v7, v87
	s_waitcnt lgkmcnt(4)
	v_mfma_f32_32x32x16_bf16 v[48:63], v[192:195], v[124:127], v[48:63]
	v_mul_f32_e32 v8, v8, v88
	v_mul_f32_e32 v9, v9, v89
	v_mul_f32_e32 v10, v10, v90
	v_mul_f32_e32 v11, v11, v91
	v_mul_f32_e32 v12, v12, v92
	v_mul_f32_e32 v13, v13, v93
	v_mul_f32_e32 v14, v14, v94
	v_mul_f32_e32 v15, v15, v95
	ds_read_b128 v[80:83], v241 offset:27840
	ds_read_b128 v[84:87], v241 offset:27872
	ds_read_b128 v[88:91], v239 offset:64
	ds_read_b128 v[92:95], v239 offset:96
	ds_read_b128 v[188:191], v241 offset:27904
	ds_read_b128 v[192:195], v241 offset:27936
	v_mfma_f32_32x32x16_bf16 v[64:79], v[128:131], v[242:245], 0
	s_waitcnt lgkmcnt(8)
	v_mul_f32_e32 v16, v16, v172
	v_mul_f32_e32 v17, v17, v173
	v_mul_f32_e32 v18, v18, v174
	v_mul_f32_e32 v19, v19, v175
	v_mul_f32_e32 v20, v20, v176
	v_mul_f32_e32 v21, v21, v177
	v_mul_f32_e32 v22, v22, v178
	v_mul_f32_e32 v23, v23, v179
	v_mfma_f32_32x32x16_bf16 v[64:79], v[124:127], v[246:249], v[64:79]
	ds_read_b128 v[172:175], v239 offset:128
	ds_read_b128 v[176:179], v239 offset:160
	ds_read_b128 v[242:245], v241 offset:27968
	ds_read_b128 v[246:249], v241 offset:28000
	s_waitcnt lgkmcnt(11)
	v_mfma_f32_32x32x16_bf16 v[64:79], v[140:143], v[180:183], v[64:79]
	ds_read_b128 v[180:183], v239 offset:192
	s_waitcnt lgkmcnt(9)
	v_mul_f32_e32 v24, v24, v80
	v_mul_f32_e32 v25, v25, v81
	v_mul_f32_e32 v26, v26, v82
	v_mul_f32_e32 v27, v27, v83
	v_mul_f32_e32 v28, v28, v84
	v_mul_f32_e32 v29, v29, v85
	v_mul_f32_e32 v30, v30, v86
	v_mul_f32_e32 v31, v31, v87
	ds_read_b128 v[80:83], v241 offset:28032
	ds_read_b128 v[84:87], v241 offset:28064
	v_mfma_f32_32x32x16_bf16 v[64:79], v[144:147], v[184:187], v[64:79]
	ds_read_b128 v[184:187], v239 offset:224
	s_waitcnt lgkmcnt(8)
	v_mul_f32_e32 v32, v32, v188
	v_mul_f32_e32 v33, v33, v189
	v_mul_f32_e32 v34, v34, v190
	v_mul_f32_e32 v35, v35, v191
	v_mul_f32_e32 v36, v36, v192
	v_mul_f32_e32 v37, v37, v193
	v_mul_f32_e32 v38, v38, v194
	v_mul_f32_e32 v39, v39, v195
	ds_read_b128 v[188:191], v241 offset:28096
	ds_read_b128 v[192:195], v241 offset:28128
	v_mfma_f32_32x32x16_bf16 v[64:79], v[148:151], v[88:91], v[64:79]
	s_waitcnt lgkmcnt(6)
	v_mul_f32_e32 v40, v40, v242
	v_mul_f32_e32 v41, v41, v243
	v_mul_f32_e32 v42, v42, v244
	v_mul_f32_e32 v43, v43, v245
	v_mul_f32_e32 v44, v44, v246
	v_mul_f32_e32 v45, v45, v247
	v_mul_f32_e32 v46, v46, v248
	v_mul_f32_e32 v47, v47, v249
	v_mfma_f32_32x32x16_bf16 v[64:79], v[152:155], v[92:95], v[64:79]
	s_waitcnt lgkmcnt(3)
	v_mul_f32_e32 v48, v48, v80
	v_mul_f32_e32 v49, v49, v81
	v_mul_f32_e32 v50, v50, v82
	v_mul_f32_e32 v51, v51, v83
	v_mul_f32_e32 v52, v52, v84
	v_mul_f32_e32 v53, v53, v85
	v_mul_f32_e32 v54, v54, v86
	v_mul_f32_e32 v55, v55, v87
	v_mfma_f32_32x32x16_bf16 v[64:79], v[156:159], v[172:175], v[64:79]
	s_waitcnt lgkmcnt(0)
	v_mul_f32_e32 v56, v56, v188
	v_mul_f32_e32 v57, v57, v189
	v_mul_f32_e32 v58, v58, v190
	v_mul_f32_e32 v59, v59, v191
	v_mul_f32_e32 v60, v60, v192
	v_mul_f32_e32 v61, v61, v193
	v_mul_f32_e32 v62, v62, v194
	v_mul_f32_e32 v63, v63, v195
	v_mfma_f32_32x32x16_bf16 v[64:79], v[160:163], v[176:179], v[64:79]
	s_mov_b32 s4, s30
	s_cmp_lt_u32 s4, 8
	s_cselect_b32 s5, 7, 0x10f
	s_sub_i32 s5, s5, s4
	s_and_b64 vcc, s[38:39], exec
	s_cselect_b32 s4, s4, s5
	s_lshl_b32 s5, s4, 5
	s_cmp_lt_i32 s4, 8
	s_cselect_b32 s4, s33, s24
	s_add_i32 s4, s4, s5
	v_or_b32_e32 v253, s4, v235
	v_mfma_f32_32x32x16_bf16 v[64:79], v[164:167], v[180:183], v[64:79]
	v_mad_u64_u32 v[254:255], s[20:21], v253, s26, v[216:217]
	v_mfma_f32_32x32x16_bf16 v[64:79], v[168:171], v[184:187], v[64:79]
	s_waitcnt vmcnt(7)
	v_mov_b64_e32 v[128:129], v[132:133]
	v_mov_b64_e32 v[130:131], v[134:135]
	v_mov_b64_e32 v[124:125], v[136:137]
	v_mov_b64_e32 v[126:127], v[138:139]
	s_add_i32 s75, s75, -1
	s_add_i32 s30, s30, 1
	s_nop 4
	v_cvt_pk_bf16_f32 v172, v64, v65
	v_cvt_pk_bf16_f32 v173, v66, v67
	v_cvt_pk_bf16_f32 v174, v68, v69
	v_cvt_pk_bf16_f32 v175, v70, v71
	v_cvt_pk_bf16_f32 v176, v72, v73
	v_cvt_pk_bf16_f32 v177, v74, v75
	v_cvt_pk_bf16_f32 v178, v76, v77
	v_cvt_pk_bf16_f32 v179, v78, v79
	global_store_dwordx2 v[254:255], v[172:173], off
	global_store_dwordx2 v[254:255], v[174:175], off offset:16
	global_store_dwordx2 v[254:255], v[176:177], off offset:32
	global_store_dwordx2 v[254:255], v[178:179], off offset:48
	s_cmpk_eq_i32 s30, 0x108
	s_waitcnt lgkmcnt(0)
	s_barrier
	s_cbranch_scc0 .Lhs_top
	s_waitcnt vmcnt(0)
	s_branch .LBB0_561

; DI void expert_dots(const Params& p, int nrows, char* smem) {
;     ...
;     const bool b0 = (i0 >> 11) == x, b1 = (i1 >> 11) == x;
;     const unsigned long long m0 = __ballot(b0), m1 = __ballot(b1);
;     const int n0 = __popcll(m0);
;     const int r0 = __builtin_amdgcn_mbcnt_hi((u32)(m0 >> 32), __builtin_amdgcn_mbcnt_lo((u32)m0, 0u));
;     const int r1 = n0 + __builtin_amdgcn_mbcnt_hi((u32)(m1 >> 32), __builtin_amdgcn_mbcnt_lo((u32)m1, 0u));
;     const int n = n0 + __popcll(m1);
;     __builtin_amdgcn_wave_barrier();
;     if (b0) list[r0] = ((u32)(2 * lane) << 16) | (u32)i0;
;     if (b1) list[r1] = ((u32)(2 * lane + 1) << 16) | (u32)i1;
;     __builtin_amdgcn_wave_barrier();
;     for (int cb = 0; cb < n; cb += 64) {
;       const int nend = min(n, cb + 64);
;       float dk = 0.f;
;       for (int base = cb; base < nend; base += 8) {
.LBB0_1081:
	s_or_b64 exec, exec, s[0:1]
	s_bcnt1_i32_b64 s0, vcc
	s_add_i32 s4, s0, s4
	s_cmp_eq_u32 s4, 0
	s_cbranch_scc1 .LBB0_1074
	v_ashrrev_i32_e32 v105, 31, v104
	s_add_i32 s5, s4, -1
	v_lshlrev_b64 v[104:105], 7, v[104:105]
	s_mov_b32 s37, 0
	s_branch .LBB0_1084

; DI void expert_dots(const Params& p, int nrows, char* smem) {
;     ...
;     f2 hf[32];
; #pragma unroll
;     for (int c = 0; c < 4; c++) {
;       const u32 hw[8] = {nh[2 * c].x, nh[2 * c].y, nh[2 * c].z, nh[2 * c].w, nh[2 * c + 1].x, nh[2 * c + 1].y, nh[2 * c + 1].z, nh[2 * c + 1].w};
; #pragma unroll
;       for (int j = 0; j < 8; j++) { hf[c * 8 + j].x = __uint_as_float(hw[j] << 16); hf[c * 8 + j].y = __uint_as_float(hw[j] & 0xffff0000u); }
;     }
;     ...
;       for (int base = cb; base < nend; base += 8) {
;         const int k0 = base + g, k1 = base + 4 + g;
;         const u32 ent0 = list[min(k0, n - 1)], ent1 = list[min(k1, n - 1)];
;         const unsigned char* ur0 = PU + (size_t)(ent0 & 0xffffu) * D;
;         const unsigned char* ur1 = PU + (size_t)(ent1 & 0xffffu) * D;
;         int4 ua[4], ub[4];
;         ua[0] = *(const int4*)(ur0); ua[1] = *(const int4*)(ur0 + 256); ua[2] = *(const int4*)(ur0 + 512); ua[3] = *(const int4*)(ur0 + 768);
;         ub[0] = *(const int4*)(ur1); ub[1] = *(const int4*)(ur1 + 256); ub[2] = *(const int4*)(ur1 + 512); ub[3] = *(const int4*)(ur1 + 768);
.LBB0_1085:
	v_add_u32_e32 v115, s33, v106
	v_add_u32_e32 v116, 4, v115
	v_min_i32_e32 v115, s5, v115
	v_lshl_add_u32 v115, v115, 2, v108
	v_min_i32_e32 v116, s5, v116
	ds_read_b32 v115, v115
	v_lshl_add_u32 v116, v116, 2, v108
	ds_read_b32 v116, v116
	s_waitcnt lgkmcnt(1)
	v_lshlrev_b32_e32 v115, 10, v115
	v_and_b32_e32 v196, 0x3fffc00, v115
	s_waitcnt lgkmcnt(0)
	v_lshlrev_b32_e32 v115, 10, v116
	v_lshl_add_u64 v[128:129], v[64:65], 0, v[196:197]
	v_and_b32_e32 v196, 0x3fffc00, v115
	v_lshl_add_u64 v[144:145], v[64:65], 0, v[196:197]
	global_load_dwordx4 v[116:119], v[128:129], off
	global_load_dwordx4 v[120:123], v[128:129], off offset:256
	global_load_dwordx4 v[124:127], v[128:129], off offset:512
	s_nop 0
	global_load_dwordx4 v[128:131], v[128:129], off offset:768
	s_nop 0
	global_load_dwordx4 v[132:135], v[144:145], off
	global_load_dwordx4 v[136:139], v[144:145], off offset:256
	global_load_dwordx4 v[140:143], v[144:145], off offset:512
	s_nop 0
	global_load_dwordx4 v[144:147], v[144:145], off offset:768
	s_cmp_lg_u32 s0, 0
	s_cbranch_scc1 .Ldp_A
	v_lshlrev_b32_e32 v72, 16, v48
	v_and_b32_e32 v73, 0xffff0000, v48
	v_lshlrev_b32_e32 v48, 16, v49
	v_and_b32_e32 v49, 0xffff0000, v49
	v_lshlrev_b32_e32 v74, 16, v50
	v_and_b32_e32 v75, 0xffff0000, v50
	v_lshlrev_b32_e32 v50, 16, v51
	v_and_b32_e32 v51, 0xffff0000, v51
	v_lshlrev_b32_e32 v76, 16, v32
	v_and_b32_e32 v77, 0xffff0000, v32
	v_lshlrev_b32_e32 v32, 16, v33
	v_and_b32_e32 v33, 0xffff0000, v33
	v_lshlrev_b32_e32 v78, 16, v34
	v_and_b32_e32 v79, 0xffff0000, v34
	v_lshlrev_b32_e32 v34, 16, v35
	v_and_b32_e32 v35, 0xffff0000, v35
	v_lshlrev_b32_e32 v80, 16, v52
	v_and_b32_e32 v81, 0xffff0000, v52
	v_lshlrev_b32_e32 v52, 16, v53
	v_and_b32_e32 v53, 0xffff0000, v53
	v_lshlrev_b32_e32 v82, 16, v54
	v_and_b32_e32 v83, 0xffff0000, v54
	v_lshlrev_b32_e32 v54, 16, v55
	v_and_b32_e32 v55, 0xffff0000, v55
	v_lshlrev_b32_e32 v84, 16, v36
	v_and_b32_e32 v85, 0xffff0000, v36
	v_lshlrev_b32_e32 v36, 16, v37
	v_and_b32_e32 v37, 0xffff0000, v37
	v_lshlrev_b32_e32 v86, 16, v38
	v_and_b32_e32 v87, 0xffff0000, v38
	v_lshlrev_b32_e32 v38, 16, v39
	v_and_b32_e32 v39, 0xffff0000, v39
	v_lshlrev_b32_e32 v88, 16, v56
	v_and_b32_e32 v89, 0xffff0000, v56
	v_lshlrev_b32_e32 v56, 16, v57
	v_and_b32_e32 v57, 0xffff0000, v57
	v_lshlrev_b32_e32 v90, 16, v58
	v_and_b32_e32 v91, 0xffff0000, v58
	v_lshlrev_b32_e32 v58, 16, v59
	v_and_b32_e32 v59, 0xffff0000, v59
	v_lshlrev_b32_e32 v92, 16, v40
	v_and_b32_e32 v93, 0xffff0000, v40
	v_lshlrev_b32_e32 v40, 16, v41
	v_and_b32_e32 v41, 0xffff0000, v41
	v_lshlrev_b32_e32 v94, 16, v42
	v_and_b32_e32 v95, 0xffff0000, v42
	v_lshlrev_b32_e32 v42, 16, v43
	v_and_b32_e32 v43, 0xffff0000, v43
	v_lshlrev_b32_e32 v96, 16, v60
	v_and_b32_e32 v97, 0xffff0000, v60
	v_lshlrev_b32_e32 v60, 16, v61
	v_and_b32_e32 v61, 0xffff0000, v61
	v_lshlrev_b32_e32 v98, 16, v62
	v_and_b32_e32 v99, 0xffff0000, v62
	v_lshlrev_b32_e32 v62, 16, v63
	v_and_b32_e32 v63, 0xffff0000, v63
	v_lshlrev_b32_e32 v100, 16, v44
	v_and_b32_e32 v101, 0xffff0000, v44
	v_lshlrev_b32_e32 v44, 16, v45
	v_and_b32_e32 v45, 0xffff0000, v45
	v_lshlrev_b32_e32 v102, 16, v46
	v_and_b32_e32 v103, 0xffff0000, v46
	v_lshlrev_b32_e32 v46, 16, v47
	v_and_b32_e32 v47, 0xffff0000, v47
